# LRU chunk prefetch: unmasked fast path for interior chunks (8 loads, one address) ; GEMM accumulator zeroing with 64-bit moves
# speedup vs baseline: 1.0113x; 1.0113x over previous
; template <class Epi, bool SP2 = false>
; __device__ __forceinline__ void gemm_phase(LAS unsigned char* lds, const Gemm g, const StaticOrder& S, const Epi& E) {
;     ...
;         const bool has_next = S.next(ui + 1, nxt);
;         const char* nA = has_next ? (const char*)g.A + (size_t)nxt.pm * tstepA : cA; const char* nB = has_next ? (const char*)g.Bt + (size_t)nxt.pn * tstepB : cB;
;     ...
; #pragma unroll
;         for (int a = 0; a < 2; ++a)
; #pragma unroll
;             for (int b = 0; b < 2; ++b)
; #pragma unroll
;                 for (int m = 0; m < 4; ++m)
; #pragma unroll
;                     for (int n = 0; n < 2; ++n) acc[a][b][m][n] = (f32x4){0.f, 0.f, 0.f, 0.f};
.LBB0_262:
	s_ashr_i32 s27, s26, 31
	s_lshl_b64 s[28:29], s[26:27], 19
	s_add_u32 s28, s14, s28
	s_addc_u32 s29, s15, s29
	s_and_b64 s[30:31], s[0:1], exec
	s_cselect_b32 s27, s29, s35
	s_cselect_b32 s67, s28, s34
	s_ashr_i32 s25, s24, 31
	s_lshl_b64 s[30:31], s[24:25], 19
	s_add_u32 s30, s92, s30
	s_addc_u32 s31, s93, s31
	s_and_b64 s[50:51], s[0:1], exec
	s_cselect_b32 s25, s31, s45
	s_cselect_b32 s72, s30, s44
	s_add_u32 s34, s34, 0x40080
	s_addc_u32 s35, s35, 0
	s_add_u32 s73, s44, 0x100
	v_mov_b64_e32 v[0:1], 0
	v_mov_b64_e32 v[2:3], 0
	v_mov_b64_e32 v[4:5], 0
	v_mov_b64_e32 v[6:7], 0
	v_mov_b64_e32 v[8:9], 0
	v_mov_b64_e32 v[10:11], 0
	v_mov_b64_e32 v[12:13], 0
	v_mov_b64_e32 v[14:15], 0
	v_mov_b64_e32 v[16:17], 0
	v_mov_b64_e32 v[18:19], 0
	v_mov_b64_e32 v[20:21], 0
	v_mov_b64_e32 v[22:23], 0
	v_mov_b64_e32 v[24:25], 0
	v_mov_b64_e32 v[26:27], 0
	v_mov_b64_e32 v[28:29], 0
	v_mov_b64_e32 v[30:31], 0
	v_mov_b64_e32 v[32:33], 0
	v_mov_b64_e32 v[34:35], 0
	v_mov_b64_e32 v[36:37], 0
	v_mov_b64_e32 v[38:39], 0
	v_mov_b64_e32 v[40:41], 0
	v_mov_b64_e32 v[42:43], 0
	v_mov_b64_e32 v[44:45], 0
	v_mov_b64_e32 v[46:47], 0
	v_mov_b64_e32 v[48:49], 0
	v_mov_b64_e32 v[50:51], 0
	v_mov_b64_e32 v[52:53], 0
	v_mov_b64_e32 v[54:55], 0
	v_mov_b64_e32 v[56:57], 0
	v_mov_b64_e32 v[58:59], 0
	v_mov_b64_e32 v[60:61], 0
	v_mov_b64_e32 v[62:63], 0
	v_mov_b64_e32 v[64:65], 0
	v_mov_b64_e32 v[66:67], 0
	v_mov_b64_e32 v[68:69], 0
	v_mov_b64_e32 v[70:71], 0
	v_mov_b64_e32 v[72:73], 0
	v_mov_b64_e32 v[74:75], 0
	v_mov_b64_e32 v[76:77], 0
	v_mov_b64_e32 v[78:79], 0
	v_mov_b64_e32 v[80:81], 0
	v_mov_b64_e32 v[82:83], 0
	v_mov_b64_e32 v[84:85], 0
	v_mov_b64_e32 v[86:87], 0
	v_mov_b64_e32 v[88:89], 0
	v_mov_b64_e32 v[90:91], 0
	v_mov_b64_e32 v[92:93], 0
	v_mov_b64_e32 v[94:95], 0
	v_mov_b64_e32 v[96:97], 0
	v_mov_b64_e32 v[98:99], 0
	v_mov_b64_e32 v[100:101], 0
	v_mov_b64_e32 v[102:103], 0
	v_mov_b64_e32 v[104:105], 0
	v_mov_b64_e32 v[106:107], 0
	v_mov_b64_e32 v[108:109], 0
	v_mov_b64_e32 v[110:111], 0
	v_mov_b64_e32 v[112:113], 0
	v_mov_b64_e32 v[114:115], 0
	v_mov_b64_e32 v[116:117], 0
	v_mov_b64_e32 v[118:119], 0
	v_mov_b64_e32 v[120:121], 0
	v_mov_b64_e32 v[122:123], 0
	v_mov_b64_e32 v[124:125], 0
	v_mov_b64_e32 v[126:127], 0
	s_addc_u32 s74, s45, 0
	s_mov_b32 s75, -2

; template <class Epi, bool SP2 = false>
; __device__ __forceinline__ void gemm_phase(LAS unsigned char* lds, const Gemm g, const StaticOrder& S, const Epi& E) {
;     ...
;         const bool has_next = S.next(ui + 1, nxt);
;         const char* nA = has_next ? (const char*)g.A + (size_t)nxt.pm * tstepA : cA; const char* nB = has_next ? (const char*)g.Bt + (size_t)nxt.pn * tstepB : cB;
;     ...
; #pragma unroll
;         for (int a = 0; a < 2; ++a)
; #pragma unroll
;             for (int b = 0; b < 2; ++b)
; #pragma unroll
;                 for (int m = 0; m < 4; ++m)
; #pragma unroll
;                     for (int n = 0; n < 2; ++n) acc[a][b][m][n] = (f32x4){0.f, 0.f, 0.f, 0.f};
.LBB0_333:
	s_add_u32 s34, s34, 0xb0080
	s_addc_u32 s35, s35, 0
	s_add_u32 s84, s52, 0x100
	v_mov_b64_e32 v[0:1], 0
	v_mov_b64_e32 v[2:3], 0
	v_mov_b64_e32 v[4:5], 0
	v_mov_b64_e32 v[6:7], 0
	v_mov_b64_e32 v[8:9], 0
	v_mov_b64_e32 v[10:11], 0
	v_mov_b64_e32 v[12:13], 0
	v_mov_b64_e32 v[14:15], 0
	v_mov_b64_e32 v[16:17], 0
	v_mov_b64_e32 v[18:19], 0
	v_mov_b64_e32 v[20:21], 0
	v_mov_b64_e32 v[22:23], 0
	v_mov_b64_e32 v[24:25], 0
	v_mov_b64_e32 v[26:27], 0
	v_mov_b64_e32 v[28:29], 0
	v_mov_b64_e32 v[30:31], 0
	v_mov_b64_e32 v[32:33], 0
	v_mov_b64_e32 v[34:35], 0
	v_mov_b64_e32 v[36:37], 0
	v_mov_b64_e32 v[38:39], 0
	v_mov_b64_e32 v[40:41], 0
	v_mov_b64_e32 v[42:43], 0
	v_mov_b64_e32 v[44:45], 0
	v_mov_b64_e32 v[46:47], 0
	v_mov_b64_e32 v[48:49], 0
	v_mov_b64_e32 v[50:51], 0
	v_mov_b64_e32 v[52:53], 0
	v_mov_b64_e32 v[54:55], 0
	v_mov_b64_e32 v[56:57], 0
	v_mov_b64_e32 v[58:59], 0
	v_mov_b64_e32 v[60:61], 0
	v_mov_b64_e32 v[62:63], 0
	v_mov_b64_e32 v[64:65], 0
	v_mov_b64_e32 v[66:67], 0
	v_mov_b64_e32 v[68:69], 0
	v_mov_b64_e32 v[70:71], 0
	v_mov_b64_e32 v[72:73], 0
	v_mov_b64_e32 v[74:75], 0
	v_mov_b64_e32 v[76:77], 0
	v_mov_b64_e32 v[78:79], 0
	v_mov_b64_e32 v[80:81], 0
	v_mov_b64_e32 v[82:83], 0
	v_mov_b64_e32 v[84:85], 0
	v_mov_b64_e32 v[86:87], 0
	v_mov_b64_e32 v[88:89], 0
	v_mov_b64_e32 v[90:91], 0
	v_mov_b64_e32 v[92:93], 0
	v_mov_b64_e32 v[94:95], 0
	v_mov_b64_e32 v[96:97], 0
	v_mov_b64_e32 v[98:99], 0
	v_mov_b64_e32 v[100:101], 0
	v_mov_b64_e32 v[102:103], 0
	v_mov_b64_e32 v[104:105], 0
	v_mov_b64_e32 v[106:107], 0
	v_mov_b64_e32 v[108:109], 0
	v_mov_b64_e32 v[110:111], 0
	v_mov_b64_e32 v[112:113], 0
	v_mov_b64_e32 v[114:115], 0
	v_mov_b64_e32 v[116:117], 0
	v_mov_b64_e32 v[118:119], 0
	v_mov_b64_e32 v[120:121], 0
	v_mov_b64_e32 v[122:123], 0
	v_mov_b64_e32 v[124:125], 0
	v_mov_b64_e32 v[126:127], 0
	s_addc_u32 s85, s53, 0
	s_mov_b32 s86, -2

; template <class Epi, bool SP2 = false>
; __device__ __forceinline__ void gemm_phase(LAS unsigned char* lds, const Gemm g, const StaticOrder& S, const Epi& E) {
;     ...
;         const bool has_next = S.next(ui + 1, nxt);
;         const char* nA = has_next ? (const char*)g.A + (size_t)nxt.pm * tstepA : cA; const char* nB = has_next ? (const char*)g.Bt + (size_t)nxt.pn * tstepB : cB;
;     ...
; #pragma unroll
;         for (int a = 0; a < 2; ++a)
; #pragma unroll
;             for (int b = 0; b < 2; ++b)
; #pragma unroll
;                 for (int m = 0; m < 4; ++m)
; #pragma unroll
;                     for (int n = 0; n < 2; ++n) acc[a][b][m][n] = (f32x4){0.f, 0.f, 0.f, 0.f};
.LBB0_461:
	s_ashr_i32 s27, s26, 31
	s_lshl_b64 s[28:29], s[26:27], 19
	s_add_u32 s28, s14, s28
	s_addc_u32 s29, s15, s29
	s_and_b64 s[40:41], s[0:1], exec
	s_cselect_b32 s5, s29, s35
	s_cselect_b32 s27, s28, s34
	s_ashr_i32 s25, s24, 31
	s_lshl_b64 s[40:41], s[24:25], 19
	s_add_u32 s40, s3, s40
	s_addc_u32 s41, s52, s41
	s_and_b64 s[50:51], s[0:1], exec
	s_cselect_b32 s25, s41, s45
	s_cselect_b32 s33, s40, s44
	s_add_u32 s34, s34, 0x40080
	s_addc_u32 s35, s35, 0
	s_add_u32 s72, s44, 0x100
	v_mov_b64_e32 v[0:1], 0
	v_mov_b64_e32 v[2:3], 0
	v_mov_b64_e32 v[4:5], 0
	v_mov_b64_e32 v[6:7], 0
	v_mov_b64_e32 v[8:9], 0
	v_mov_b64_e32 v[10:11], 0
	v_mov_b64_e32 v[12:13], 0
	v_mov_b64_e32 v[14:15], 0
	v_mov_b64_e32 v[16:17], 0
	v_mov_b64_e32 v[18:19], 0
	v_mov_b64_e32 v[20:21], 0
	v_mov_b64_e32 v[22:23], 0
	v_mov_b64_e32 v[24:25], 0
	v_mov_b64_e32 v[26:27], 0
	v_mov_b64_e32 v[28:29], 0
	v_mov_b64_e32 v[30:31], 0
	v_mov_b64_e32 v[32:33], 0
	v_mov_b64_e32 v[34:35], 0
	v_mov_b64_e32 v[36:37], 0
	v_mov_b64_e32 v[38:39], 0
	v_mov_b64_e32 v[40:41], 0
	v_mov_b64_e32 v[42:43], 0
	v_mov_b64_e32 v[44:45], 0
	v_mov_b64_e32 v[46:47], 0
	v_mov_b64_e32 v[48:49], 0
	v_mov_b64_e32 v[50:51], 0
	v_mov_b64_e32 v[52:53], 0
	v_mov_b64_e32 v[54:55], 0
	v_mov_b64_e32 v[56:57], 0
	v_mov_b64_e32 v[58:59], 0
	v_mov_b64_e32 v[60:61], 0
	v_mov_b64_e32 v[62:63], 0
	v_mov_b64_e32 v[64:65], 0
	v_mov_b64_e32 v[66:67], 0
	v_mov_b64_e32 v[68:69], 0
	v_mov_b64_e32 v[70:71], 0
	v_mov_b64_e32 v[72:73], 0
	v_mov_b64_e32 v[74:75], 0
	v_mov_b64_e32 v[76:77], 0
	v_mov_b64_e32 v[78:79], 0
	v_mov_b64_e32 v[80:81], 0
	v_mov_b64_e32 v[82:83], 0
	v_mov_b64_e32 v[84:85], 0
	v_mov_b64_e32 v[86:87], 0
	v_mov_b64_e32 v[88:89], 0
	v_mov_b64_e32 v[90:91], 0
	v_mov_b64_e32 v[92:93], 0
	v_mov_b64_e32 v[94:95], 0
	v_mov_b64_e32 v[96:97], 0
	v_mov_b64_e32 v[98:99], 0
	v_mov_b64_e32 v[100:101], 0
	v_mov_b64_e32 v[102:103], 0
	v_mov_b64_e32 v[104:105], 0
	v_mov_b64_e32 v[106:107], 0
	v_mov_b64_e32 v[108:109], 0
	v_mov_b64_e32 v[110:111], 0
	v_mov_b64_e32 v[112:113], 0
	v_mov_b64_e32 v[114:115], 0
	v_mov_b64_e32 v[116:117], 0
	v_mov_b64_e32 v[118:119], 0
	v_mov_b64_e32 v[120:121], 0
	v_mov_b64_e32 v[122:123], 0
	v_mov_b64_e32 v[124:125], 0
	v_mov_b64_e32 v[126:127], 0
	s_addc_u32 s73, s45, 0
	s_mov_b32 s74, -2

; #define LAS __attribute__((address_space(3)))
; __device__ __forceinline__ unsigned pk_bf16(float lo, float hi) { const f32x2 v = {lo, hi}; const bf16x2_t b = __builtin_convertvector(v, bf16x2_t); return __builtin_bit_cast(unsigned, b); }
; __device__ __forceinline__ float lo_bf(unsigned w) { return __uint_as_float(w << 16); }
; __device__ __forceinline__ float hi_bf(unsigned w) { return __uint_as_float(w & 0xffff0000u); }
; #define LRU_PREFETCH(CI) do { const int _cc = d ? (nch - 1 - (CI)) : (CI); _Pragma("unroll") for (int hf = 0; hf < 2; ++hf) _Pragma("unroll") for (int j = 0; j < 4; ++j) { \
;                 const int tt = _cc * 64 + tr + 32 * hf + j - 1; pw[hf][j] = (tt >= 0 && tt < S) ? *(const u32x4*)(XL + (size_t)(row0 + tt) * D + c0) : (u32x4){0u, 0u, 0u, 0u}; } } while (0)
; __device__ __forceinline__ void phase_lru(const Params& p, LAS unsigned char* lds) {
;     ...
;             LRU_PREFETCH(0);
;             for (int ci = 0; ci < nch; ++ci) {
;                 const int cc = d ? (nch - 1 - ci) : ci, t0 = cc * 64;
;                 __syncthreads();
; #pragma unroll
;                 for (int hf = 0; hf < 2; ++hf) {
;                     const int tl = tr + 32 * hf;
;                     float a[8];
; #pragma unroll
;                     for (int e = 0; e < 8; ++e) a[e] = cb[e];
; #pragma unroll
;                     for (int j = 0; j < 4; ++j) { const u32x4 w = pw[hf][j];
;                         a[0] += cw[j][0] * lo_bf(w.x); a[1] += cw[j][1] * hi_bf(w.x); a[2] += cw[j][2] * lo_bf(w.y); a[3] += cw[j][3] * hi_bf(w.y);
;                         a[4] += cw[j][4] * lo_bf(w.z); a[5] += cw[j][5] * hi_bf(w.z); a[6] += cw[j][6] * lo_bf(w.w); a[7] += cw[j][7] * hi_bf(w.w); }
;                     u32x4 o; o.x = pk_bf16(a[0], a[1]); o.y = pk_bf16(a[2], a[3]); o.z = pk_bf16(a[4], a[5]); o.w = pk_bf16(a[6], a[7]);
;                     *(LAS u32x4*)(lds + tl * XC_PITCH + cgp * 2) = o;
;                 }
;                 __syncthreads();
;                 if (ci + 1 < nch) LRU_PREFETCH(ci + 1);
.LBB0_574:
	s_waitcnt vmcnt(0)
	v_lshlrev_b32_e32 v2, 16, v76
	v_and_b32_e32 v3, 0xffff0000, v76
	v_pk_fma_f32 v[2:3], v[28:29], v[2:3], v[32:33]
	v_lshlrev_b32_e32 v108, 16, v80
	v_and_b32_e32 v109, 0xffff0000, v80
	v_pk_fma_f32 v[2:3], v[4:5], v[108:109], v[2:3]
	v_lshlrev_b32_e32 v108, 16, v84
	v_and_b32_e32 v109, 0xffff0000, v84
	v_pk_fma_f32 v[2:3], v[8:9], v[108:109], v[2:3]
	v_lshlrev_b32_e32 v108, 16, v88
	v_and_b32_e32 v109, 0xffff0000, v88
	v_pk_fma_f32 v[2:3], v[20:21], v[108:109], v[2:3]
	v_lshlrev_b32_e32 v108, 16, v77
	v_and_b32_e32 v109, 0xffff0000, v77
	v_pk_fma_f32 v[108:109], v[30:31], v[108:109], v[34:35]
	v_lshlrev_b32_e32 v110, 16, v81
	v_and_b32_e32 v111, 0xffff0000, v81
	v_pk_fma_f32 v[108:109], v[6:7], v[110:111], v[108:109]
	v_lshlrev_b32_e32 v110, 16, v85
	v_and_b32_e32 v111, 0xffff0000, v85
	v_pk_fma_f32 v[108:109], v[10:11], v[110:111], v[108:109]
	v_lshlrev_b32_e32 v110, 16, v89
	v_and_b32_e32 v111, 0xffff0000, v89
	v_pk_fma_f32 v[110:111], v[22:23], v[110:111], v[108:109]
	v_lshlrev_b32_e32 v108, 16, v78
	v_and_b32_e32 v109, 0xffff0000, v78
	v_pk_fma_f32 v[108:109], v[36:37], v[108:109], v[40:41]
	v_lshlrev_b32_e32 v112, 16, v82
	v_and_b32_e32 v113, 0xffff0000, v82
	v_pk_fma_f32 v[108:109], v[12:13], v[112:113], v[108:109]
	v_lshlrev_b32_e32 v112, 16, v86
	v_and_b32_e32 v113, 0xffff0000, v86
	v_pk_fma_f32 v[108:109], v[16:17], v[112:113], v[108:109]
	v_lshlrev_b32_e32 v112, 16, v90
	v_and_b32_e32 v113, 0xffff0000, v90
	v_pk_fma_f32 v[112:113], v[24:25], v[112:113], v[108:109]
	v_lshlrev_b32_e32 v108, 16, v79
	v_and_b32_e32 v109, 0xffff0000, v79
	v_pk_fma_f32 v[108:109], v[38:39], v[108:109], v[42:43]
	v_lshlrev_b32_e32 v114, 16, v83
	v_and_b32_e32 v115, 0xffff0000, v83
	v_pk_fma_f32 v[108:109], v[14:15], v[114:115], v[108:109]
	v_lshlrev_b32_e32 v114, 16, v87
	v_and_b32_e32 v115, 0xffff0000, v87
	v_pk_fma_f32 v[108:109], v[18:19], v[114:115], v[108:109]
	v_lshlrev_b32_e32 v114, 16, v91
	v_and_b32_e32 v115, 0xffff0000, v91
	v_pk_fma_f32 v[114:115], v[26:27], v[114:115], v[108:109]
	v_cvt_pk_bf16_f32 v108, v2, v3
	v_cvt_pk_bf16_f32 v109, v110, v111
	v_cvt_pk_bf16_f32 v110, v112, v113
	v_cvt_pk_bf16_f32 v111, v114, v115
	v_lshlrev_b32_e32 v2, 16, v92
	v_and_b32_e32 v3, 0xffff0000, v92
	s_barrier
	ds_write_b128 v191, v[108:111]
	v_pk_fma_f32 v[2:3], v[28:29], v[2:3], v[32:33]
	v_lshlrev_b32_e32 v108, 16, v96
	v_and_b32_e32 v109, 0xffff0000, v96
	v_pk_fma_f32 v[2:3], v[4:5], v[108:109], v[2:3]
	v_lshlrev_b32_e32 v108, 16, v100
	v_and_b32_e32 v109, 0xffff0000, v100
	v_pk_fma_f32 v[2:3], v[8:9], v[108:109], v[2:3]
	v_lshlrev_b32_e32 v108, 16, v104
	v_and_b32_e32 v109, 0xffff0000, v104
	v_pk_fma_f32 v[2:3], v[20:21], v[108:109], v[2:3]
	v_lshlrev_b32_e32 v108, 16, v93
	v_and_b32_e32 v109, 0xffff0000, v93
	v_pk_fma_f32 v[108:109], v[30:31], v[108:109], v[34:35]
	v_lshlrev_b32_e32 v110, 16, v97
	v_and_b32_e32 v111, 0xffff0000, v97
	v_pk_fma_f32 v[108:109], v[6:7], v[110:111], v[108:109]
	v_lshlrev_b32_e32 v110, 16, v101
	v_and_b32_e32 v111, 0xffff0000, v101
	v_pk_fma_f32 v[108:109], v[10:11], v[110:111], v[108:109]
	v_lshlrev_b32_e32 v110, 16, v105
	v_and_b32_e32 v111, 0xffff0000, v105
	v_pk_fma_f32 v[110:111], v[22:23], v[110:111], v[108:109]
	v_lshlrev_b32_e32 v108, 16, v94
	v_and_b32_e32 v109, 0xffff0000, v94
	v_pk_fma_f32 v[108:109], v[36:37], v[108:109], v[40:41]
	v_lshlrev_b32_e32 v112, 16, v98
	v_and_b32_e32 v113, 0xffff0000, v98
	v_pk_fma_f32 v[108:109], v[12:13], v[112:113], v[108:109]
	v_lshlrev_b32_e32 v112, 16, v102
	v_and_b32_e32 v113, 0xffff0000, v102
	v_pk_fma_f32 v[108:109], v[16:17], v[112:113], v[108:109]
	v_lshlrev_b32_e32 v112, 16, v106
	v_and_b32_e32 v113, 0xffff0000, v106
	v_pk_fma_f32 v[112:113], v[24:25], v[112:113], v[108:109]
	v_lshlrev_b32_e32 v108, 16, v95
	v_and_b32_e32 v109, 0xffff0000, v95
	v_pk_fma_f32 v[108:109], v[38:39], v[108:109], v[42:43]
	v_lshlrev_b32_e32 v114, 16, v99
	v_and_b32_e32 v115, 0xffff0000, v99
	v_pk_fma_f32 v[108:109], v[14:15], v[114:115], v[108:109]
	v_lshlrev_b32_e32 v114, 16, v103
	v_and_b32_e32 v115, 0xffff0000, v103
	v_pk_fma_f32 v[108:109], v[18:19], v[114:115], v[108:109]
	v_lshlrev_b32_e32 v114, 16, v107
	v_and_b32_e32 v115, 0xffff0000, v107
	v_pk_fma_f32 v[114:115], v[26:27], v[114:115], v[108:109]
	v_cvt_pk_bf16_f32 v108, v2, v3
	v_cvt_pk_bf16_f32 v109, v110, v111
	v_cvt_pk_bf16_f32 v110, v112, v113
	v_cvt_pk_bf16_f32 v111, v114, v115
	s_cmp_ge_u32 s10, s79
	ds_write_b128 v191, v[108:111] offset:8704
	s_waitcnt lgkmcnt(0)
	s_barrier
	s_cbranch_scc1 .LBB0_592
	s_add_i32 s33, s88, -1
	s_and_b64 s[8:9], s[52:53], exec
	s_cselect_b32 s33, s10, s33
	s_cmp_lt_i32 s33, 1
	s_cbranch_scc1 .Llru_pf_slow
	s_lshr_b32 s32, s78, 6
	s_add_i32 s32, s32, -1
	s_cmp_ge_i32 s33, s32
	s_cbranch_scc1 .Llru_pf_slow
	v_lshl_or_b32 v1, s33, 6, v184
	v_add_u32_e32 v2, s77, v1
	v_add_u32_e32 v2, 1, v2
	v_ashrrev_i32_e32 v3, 31, v2
	v_lshlrev_b64 v[2:3], 11, v[2:3]
	v_lshl_add_u64 v[2:3], v[120:121], 0, v[2:3]
	s_mov_b64 s[68:69], 0x10000
	v_lshl_add_u64 v[108:109], v[2:3], 0, s[68:69]
	global_load_dwordx4 v[76:79], v[2:3], off offset:-4096
	global_load_dwordx4 v[80:83], v[2:3], off offset:-2048
	global_load_dwordx4 v[84:87], v[2:3], off
	global_load_dwordx4 v[88:91], v[2:3], off offset:2048
	global_load_dwordx4 v[92:95], v[108:109], off offset:-4096
	global_load_dwordx4 v[96:99], v[108:109], off offset:-2048
	global_load_dwordx4 v[100:103], v[108:109], off
	global_load_dwordx4 v[104:107], v[108:109], off offset:2048
	s_branch .LBB0_592
.Llru_pf_slow:
	s_add_i32 s33, s88, -1
	s_and_b64 s[8:9], s[52:53], exec
	s_cselect_b32 s33, s10, s33
	v_lshl_or_b32 v104, s33, 6, v184
	v_mov_b32_e32 v80, v0
	v_mov_b32_e32 v81, v0
	v_cmp_lt_i32_e32 vcc, 0, v104
	v_cmp_ge_i32_e64 s[8:9], s78, v104
	v_mov_b32_e32 v82, v0
	v_mov_b32_e32 v83, v0
	v_mov_b64_e32 v[76:77], v[80:81]
	s_and_b64 s[68:69], vcc, s[8:9]
	v_mov_b64_e32 v[78:79], v[82:83]
	s_and_saveexec_b64 s[8:9], s[68:69]
	s_cbranch_execz .LBB0_577
	v_add_u32_e32 v2, s82, v104
	v_ashrrev_i32_e32 v3, 31, v2
	v_lshlrev_b64 v[2:3], 11, v[2:3]
	v_lshl_add_u64 v[2:3], v[120:121], 0, v[2:3]
	global_load_dwordx4 v[76:79], v[2:3], off

; template <class Epi, bool SP2 = false>
; __device__ __forceinline__ void gemm_phase(LAS unsigned char* lds, const Gemm g, const StaticOrder& S, const Epi& E) {
;     ...
;         const bool has_next = S.next(ui + 1, nxt);
;         const char* nA = has_next ? (const char*)g.A + (size_t)nxt.pm * tstepA : cA; const char* nB = has_next ? (const char*)g.Bt + (size_t)nxt.pn * tstepB : cB;
;     ...
; #pragma unroll
;         for (int a = 0; a < 2; ++a)
; #pragma unroll
;             for (int b = 0; b < 2; ++b)
; #pragma unroll
;                 for (int m = 0; m < 4; ++m)
; #pragma unroll
;                     for (int n = 0; n < 2; ++n) acc[a][b][m][n] = (f32x4){0.f, 0.f, 0.f, 0.f};
.LBB0_804:
	s_ashr_i32 s43, s42, 31
	s_lshl_b64 s[44:45], s[42:43], 19
	s_add_u32 s44, s14, s44
	s_addc_u32 s45, s15, s45
	s_and_b64 s[46:47], s[0:1], exec
	s_cselect_b32 s43, s45, s35
	s_cselect_b32 s76, s44, s34
	s_ashr_i32 s41, s40, 31
	s_lshl_b64 s[46:47], s[40:41], 19
	s_add_u32 s46, s3, s46
	s_addc_u32 s47, s52, s47
	s_and_b64 s[50:51], s[0:1], exec
	s_cselect_b32 s41, s47, s49
	s_cselect_b32 s77, s46, s48
	s_add_u32 s34, s34, 0x40080
	s_addc_u32 s35, s35, 0
	s_add_u32 s78, s48, 0x100
	v_mov_b64_e32 v[0:1], 0
	v_mov_b64_e32 v[2:3], 0
	v_mov_b64_e32 v[4:5], 0
	v_mov_b64_e32 v[6:7], 0
	v_mov_b64_e32 v[8:9], 0
	v_mov_b64_e32 v[10:11], 0
	v_mov_b64_e32 v[12:13], 0
	v_mov_b64_e32 v[14:15], 0
	v_mov_b64_e32 v[16:17], 0
	v_mov_b64_e32 v[18:19], 0
	v_mov_b64_e32 v[20:21], 0
	v_mov_b64_e32 v[22:23], 0
	v_mov_b64_e32 v[24:25], 0
	v_mov_b64_e32 v[26:27], 0
	v_mov_b64_e32 v[28:29], 0
	v_mov_b64_e32 v[30:31], 0
	v_mov_b64_e32 v[32:33], 0
	v_mov_b64_e32 v[34:35], 0
	v_mov_b64_e32 v[36:37], 0
	v_mov_b64_e32 v[38:39], 0
	v_mov_b64_e32 v[40:41], 0
	v_mov_b64_e32 v[42:43], 0
	v_mov_b64_e32 v[44:45], 0
	v_mov_b64_e32 v[46:47], 0
	v_mov_b64_e32 v[48:49], 0
	v_mov_b64_e32 v[50:51], 0
	v_mov_b64_e32 v[52:53], 0
	v_mov_b64_e32 v[54:55], 0
	v_mov_b64_e32 v[56:57], 0
	v_mov_b64_e32 v[58:59], 0
	v_mov_b64_e32 v[60:61], 0
	v_mov_b64_e32 v[62:63], 0
	v_mov_b64_e32 v[64:65], 0
	v_mov_b64_e32 v[66:67], 0
	v_mov_b64_e32 v[68:69], 0
	v_mov_b64_e32 v[70:71], 0
	v_mov_b64_e32 v[72:73], 0
	v_mov_b64_e32 v[74:75], 0
	v_mov_b64_e32 v[76:77], 0
	v_mov_b64_e32 v[78:79], 0
	v_mov_b64_e32 v[80:81], 0
	v_mov_b64_e32 v[82:83], 0
	v_mov_b64_e32 v[84:85], 0
	v_mov_b64_e32 v[86:87], 0
	v_mov_b64_e32 v[88:89], 0
	v_mov_b64_e32 v[90:91], 0
	v_mov_b64_e32 v[92:93], 0
	v_mov_b64_e32 v[94:95], 0
	v_mov_b64_e32 v[96:97], 0
	v_mov_b64_e32 v[98:99], 0
	v_mov_b64_e32 v[100:101], 0
	v_mov_b64_e32 v[102:103], 0
	v_mov_b64_e32 v[104:105], 0
	v_mov_b64_e32 v[106:107], 0
	v_mov_b64_e32 v[108:109], 0
	v_mov_b64_e32 v[110:111], 0
	v_mov_b64_e32 v[112:113], 0
	v_mov_b64_e32 v[114:115], 0
	v_mov_b64_e32 v[116:117], 0
	v_mov_b64_e32 v[118:119], 0
	v_mov_b64_e32 v[120:121], 0
	v_mov_b64_e32 v[122:123], 0
	v_mov_b64_e32 v[124:125], 0
	v_mov_b64_e32 v[126:127], 0
	s_addc_u32 s79, s49, 0
	s_mov_b32 s80, -2

; template <class Epi, bool SP2 = false>
; __device__ __forceinline__ void gemm_phase(LAS unsigned char* lds, const Gemm g, const StaticOrder& S, const Epi& E) {
;     ...
;         const bool has_next = S.next(ui + 1, nxt);
;         const char* nA = has_next ? (const char*)g.A + (size_t)nxt.pm * tstepA : cA; const char* nB = has_next ? (const char*)g.Bt + (size_t)nxt.pn * tstepB : cB;
;     ...
; #pragma unroll
;         for (int a = 0; a < 2; ++a)
; #pragma unroll
;             for (int b = 0; b < 2; ++b)
; #pragma unroll
;                 for (int m = 0; m < 4; ++m)
; #pragma unroll
;                     for (int n = 0; n < 2; ++n) acc[a][b][m][n] = (f32x4){0.f, 0.f, 0.f, 0.f};
.LBB0_871:
	s_ashr_i32 s45, s44, 31
	s_lshl_b64 s[46:47], s[44:45], 18
	s_add_u32 s46, s16, s46
	s_addc_u32 s47, s17, s47
	s_and_b64 s[48:49], s[0:1], exec
	s_cselect_b32 s45, s47, s35
	s_cselect_b32 s78, s46, s34
	s_ashr_i32 s43, s42, 31
	s_lshl_b64 s[48:49], s[42:43], 18
	s_add_u32 s48, s3, s48
	s_addc_u32 s49, s54, s49
	s_and_b64 s[52:53], s[0:1], exec
	s_cselect_b32 s43, s49, s51
	s_cselect_b32 s79, s48, s50
	s_add_u32 s34, s34, 0x20080
	s_addc_u32 s35, s35, 0
	s_add_u32 s80, s50, 0x100
	v_mov_b64_e32 v[0:1], 0
	v_mov_b64_e32 v[2:3], 0
	v_mov_b64_e32 v[4:5], 0
	v_mov_b64_e32 v[6:7], 0
	v_mov_b64_e32 v[8:9], 0
	v_mov_b64_e32 v[10:11], 0
	v_mov_b64_e32 v[12:13], 0
	v_mov_b64_e32 v[14:15], 0
	v_mov_b64_e32 v[16:17], 0
	v_mov_b64_e32 v[18:19], 0
	v_mov_b64_e32 v[20:21], 0
	v_mov_b64_e32 v[22:23], 0
	v_mov_b64_e32 v[24:25], 0
	v_mov_b64_e32 v[26:27], 0
	v_mov_b64_e32 v[28:29], 0
	v_mov_b64_e32 v[30:31], 0
	v_mov_b64_e32 v[32:33], 0
	v_mov_b64_e32 v[34:35], 0
	v_mov_b64_e32 v[36:37], 0
	v_mov_b64_e32 v[38:39], 0
	v_mov_b64_e32 v[40:41], 0
	v_mov_b64_e32 v[42:43], 0
	v_mov_b64_e32 v[44:45], 0
	v_mov_b64_e32 v[46:47], 0
	v_mov_b64_e32 v[48:49], 0
	v_mov_b64_e32 v[50:51], 0
	v_mov_b64_e32 v[52:53], 0
	v_mov_b64_e32 v[54:55], 0
	v_mov_b64_e32 v[56:57], 0
	v_mov_b64_e32 v[58:59], 0
	v_mov_b64_e32 v[60:61], 0
	v_mov_b64_e32 v[62:63], 0
	v_mov_b64_e32 v[64:65], 0
	v_mov_b64_e32 v[66:67], 0
	v_mov_b64_e32 v[68:69], 0
	v_mov_b64_e32 v[70:71], 0
	v_mov_b64_e32 v[72:73], 0
	v_mov_b64_e32 v[74:75], 0
	v_mov_b64_e32 v[76:77], 0
	v_mov_b64_e32 v[78:79], 0
	v_mov_b64_e32 v[80:81], 0
	v_mov_b64_e32 v[82:83], 0
	v_mov_b64_e32 v[84:85], 0
	v_mov_b64_e32 v[86:87], 0
	v_mov_b64_e32 v[88:89], 0
	v_mov_b64_e32 v[90:91], 0
	v_mov_b64_e32 v[92:93], 0
	v_mov_b64_e32 v[94:95], 0
	v_mov_b64_e32 v[96:97], 0
	v_mov_b64_e32 v[98:99], 0
	v_mov_b64_e32 v[100:101], 0
	v_mov_b64_e32 v[102:103], 0
	v_mov_b64_e32 v[104:105], 0
	v_mov_b64_e32 v[106:107], 0
	v_mov_b64_e32 v[108:109], 0
	v_mov_b64_e32 v[110:111], 0
	v_mov_b64_e32 v[112:113], 0
	v_mov_b64_e32 v[114:115], 0
	v_mov_b64_e32 v[116:117], 0
	v_mov_b64_e32 v[118:119], 0
	v_mov_b64_e32 v[120:121], 0
	v_mov_b64_e32 v[122:123], 0
	v_mov_b64_e32 v[124:125], 0
	v_mov_b64_e32 v[126:127], 0
	s_addc_u32 s81, s51, 0
	s_mov_b32 s82, -2
	s_waitcnt vmcnt(0)

; template <class Epi, bool SP2 = false>
; __device__ __forceinline__ void gemm_phase(LAS unsigned char* lds, const Gemm g, const StaticOrder& S, const Epi& E) {
;     ...
;         const bool has_next = S.next(ui + 1, nxt);
;         const char* nA = has_next ? (const char*)g.A + (size_t)nxt.pm * tstepA : cA; const char* nB = has_next ? (const char*)g.Bt + (size_t)nxt.pn * tstepB : cB;
;     ...
; #pragma unroll
;         for (int a = 0; a < 2; ++a)
; #pragma unroll
;             for (int b = 0; b < 2; ++b)
; #pragma unroll
;                 for (int m = 0; m < 4; ++m)
; #pragma unroll
;                     for (int n = 0; n < 2; ++n) acc[a][b][m][n] = (f32x4){0.f, 0.f, 0.f, 0.f};
.LBB0_887:
	s_ashr_i32 s43, s42, 31
	s_lshl_b64 s[44:45], s[42:43], 19
	s_add_u32 s44, s26, s44
	s_addc_u32 s45, s27, s45
	s_and_b64 s[46:47], s[0:1], exec
	s_cselect_b32 s43, s45, s35
	s_cselect_b32 s72, s44, s34
	s_ashr_i32 s41, s40, 31
	s_lshl_b64 s[46:47], s[40:41], 19
	s_add_u32 s46, s3, s46
	s_addc_u32 s47, s52, s47
	s_and_b64 s[50:51], s[0:1], exec
	s_cselect_b32 s41, s47, s49
	s_cselect_b32 s73, s46, s48
	s_add_u32 s34, s34, 0x40080
	s_addc_u32 s35, s35, 0
	s_add_u32 s74, s48, 0x100
	v_mov_b64_e32 v[0:1], 0
	v_mov_b64_e32 v[2:3], 0
	v_mov_b64_e32 v[4:5], 0
	v_mov_b64_e32 v[6:7], 0
	v_mov_b64_e32 v[8:9], 0
	v_mov_b64_e32 v[10:11], 0
	v_mov_b64_e32 v[12:13], 0
	v_mov_b64_e32 v[14:15], 0
	v_mov_b64_e32 v[16:17], 0
	v_mov_b64_e32 v[18:19], 0
	v_mov_b64_e32 v[20:21], 0
	v_mov_b64_e32 v[22:23], 0
	v_mov_b64_e32 v[24:25], 0
	v_mov_b64_e32 v[26:27], 0
	v_mov_b64_e32 v[28:29], 0
	v_mov_b64_e32 v[30:31], 0
	v_mov_b64_e32 v[32:33], 0
	v_mov_b64_e32 v[34:35], 0
	v_mov_b64_e32 v[36:37], 0
	v_mov_b64_e32 v[38:39], 0
	v_mov_b64_e32 v[40:41], 0
	v_mov_b64_e32 v[42:43], 0
	v_mov_b64_e32 v[44:45], 0
	v_mov_b64_e32 v[46:47], 0
	v_mov_b64_e32 v[48:49], 0
	v_mov_b64_e32 v[50:51], 0
	v_mov_b64_e32 v[52:53], 0
	v_mov_b64_e32 v[54:55], 0
	v_mov_b64_e32 v[56:57], 0
	v_mov_b64_e32 v[58:59], 0
	v_mov_b64_e32 v[60:61], 0
	v_mov_b64_e32 v[62:63], 0
	v_mov_b64_e32 v[64:65], 0
	v_mov_b64_e32 v[66:67], 0
	v_mov_b64_e32 v[68:69], 0
	v_mov_b64_e32 v[70:71], 0
	v_mov_b64_e32 v[72:73], 0
	v_mov_b64_e32 v[74:75], 0
	v_mov_b64_e32 v[76:77], 0
	v_mov_b64_e32 v[78:79], 0
	v_mov_b64_e32 v[80:81], 0
	v_mov_b64_e32 v[82:83], 0
	v_mov_b64_e32 v[84:85], 0
	v_mov_b64_e32 v[86:87], 0
	v_mov_b64_e32 v[88:89], 0
	v_mov_b64_e32 v[90:91], 0
	v_mov_b64_e32 v[92:93], 0
	v_mov_b64_e32 v[94:95], 0
	v_mov_b64_e32 v[96:97], 0
	v_mov_b64_e32 v[98:99], 0
	v_mov_b64_e32 v[100:101], 0
	v_mov_b64_e32 v[102:103], 0
	v_mov_b64_e32 v[104:105], 0
	v_mov_b64_e32 v[106:107], 0
	v_mov_b64_e32 v[108:109], 0
	v_mov_b64_e32 v[110:111], 0
	v_mov_b64_e32 v[112:113], 0
	v_mov_b64_e32 v[114:115], 0
	v_mov_b64_e32 v[116:117], 0
	v_mov_b64_e32 v[118:119], 0
	v_mov_b64_e32 v[120:121], 0
	v_mov_b64_e32 v[122:123], 0
	v_mov_b64_e32 v[124:125], 0
	v_mov_b64_e32 v[126:127], 0
	s_addc_u32 s75, s49, 0
	s_mov_b32 s76, -2
	s_waitcnt vmcnt(0)

; template <class Epi, bool SP2 = false>
; __device__ __forceinline__ void gemm_phase(LAS unsigned char* lds, const Gemm g, const StaticOrder& S, const Epi& E) {
;     ...
;         const bool has_next = S.next(ui + 1, nxt);
;         const char* nA = has_next ? (const char*)g.A + (size_t)nxt.pm * tstepA : cA; const char* nB = has_next ? (const char*)g.Bt + (size_t)nxt.pn * tstepB : cB;
;     ...
; #pragma unroll
;         for (int a = 0; a < 2; ++a)
; #pragma unroll
;             for (int b = 0; b < 2; ++b)
; #pragma unroll
;                 for (int m = 0; m < 4; ++m)
; #pragma unroll
;                     for (int n = 0; n < 2; ++n) acc[a][b][m][n] = (f32x4){0.f, 0.f, 0.f, 0.f};
.LBB0_954:
	s_ashr_i32 s41, s40, 31
	s_lshl_b64 s[42:43], s[40:41], 19
	s_add_u32 s42, s24, s42
	s_addc_u32 s43, s25, s43
	s_and_b64 s[44:45], s[0:1], exec
	s_cselect_b32 s41, s43, s35
	s_cselect_b32 s74, s42, s34
	s_ashr_i32 s39, s38, 31
	s_lshl_b64 s[44:45], s[38:39], 19
	s_add_u32 s44, s3, s44
	s_addc_u32 s45, s33, s45
	s_and_b64 s[48:49], s[0:1], exec
	s_cselect_b32 s39, s45, s47
	s_cselect_b32 s75, s44, s46
	s_add_u32 s34, s34, 0x40080
	s_addc_u32 s35, s35, 0
	s_add_u32 s76, s46, 0x100
	v_mov_b64_e32 v[0:1], 0
	v_mov_b64_e32 v[2:3], 0
	v_mov_b64_e32 v[4:5], 0
	v_mov_b64_e32 v[6:7], 0
	v_mov_b64_e32 v[8:9], 0
	v_mov_b64_e32 v[10:11], 0
	v_mov_b64_e32 v[12:13], 0
	v_mov_b64_e32 v[14:15], 0
	v_mov_b64_e32 v[16:17], 0
	v_mov_b64_e32 v[18:19], 0
	v_mov_b64_e32 v[20:21], 0
	v_mov_b64_e32 v[22:23], 0
	v_mov_b64_e32 v[24:25], 0
	v_mov_b64_e32 v[26:27], 0
	v_mov_b64_e32 v[28:29], 0
	v_mov_b64_e32 v[30:31], 0
	v_mov_b64_e32 v[32:33], 0
	v_mov_b64_e32 v[34:35], 0
	v_mov_b64_e32 v[36:37], 0
	v_mov_b64_e32 v[38:39], 0
	v_mov_b64_e32 v[40:41], 0
	v_mov_b64_e32 v[42:43], 0
	v_mov_b64_e32 v[44:45], 0
	v_mov_b64_e32 v[46:47], 0
	v_mov_b64_e32 v[48:49], 0
	v_mov_b64_e32 v[50:51], 0
	v_mov_b64_e32 v[52:53], 0
	v_mov_b64_e32 v[54:55], 0
	v_mov_b64_e32 v[56:57], 0
	v_mov_b64_e32 v[58:59], 0
	v_mov_b64_e32 v[60:61], 0
	v_mov_b64_e32 v[62:63], 0
	v_mov_b64_e32 v[64:65], 0
	v_mov_b64_e32 v[66:67], 0
	v_mov_b64_e32 v[68:69], 0
	v_mov_b64_e32 v[70:71], 0
	v_mov_b64_e32 v[72:73], 0
	v_mov_b64_e32 v[74:75], 0
	v_mov_b64_e32 v[76:77], 0
	v_mov_b64_e32 v[78:79], 0
	v_mov_b64_e32 v[80:81], 0
	v_mov_b64_e32 v[82:83], 0
	v_mov_b64_e32 v[84:85], 0
	v_mov_b64_e32 v[86:87], 0
	v_mov_b64_e32 v[88:89], 0
	v_mov_b64_e32 v[90:91], 0
	v_mov_b64_e32 v[92:93], 0
	v_mov_b64_e32 v[94:95], 0
	v_mov_b64_e32 v[96:97], 0
	v_mov_b64_e32 v[98:99], 0
	v_mov_b64_e32 v[100:101], 0
	v_mov_b64_e32 v[102:103], 0
	v_mov_b64_e32 v[104:105], 0
	v_mov_b64_e32 v[106:107], 0
	v_mov_b64_e32 v[108:109], 0
	v_mov_b64_e32 v[110:111], 0
	v_mov_b64_e32 v[112:113], 0
	v_mov_b64_e32 v[114:115], 0
	v_mov_b64_e32 v[116:117], 0
	v_mov_b64_e32 v[118:119], 0
	v_mov_b64_e32 v[120:121], 0
	v_mov_b64_e32 v[122:123], 0
	v_mov_b64_e32 v[124:125], 0
	v_mov_b64_e32 v[126:127], 0
	s_addc_u32 s77, s47, 0
	s_mov_b32 s78, -2

; template <class Epi, bool SP2 = false>
; __device__ __forceinline__ void gemm_phase(LAS unsigned char* lds, const Gemm g, const StaticOrder& S, const Epi& E) {
;     ...
;         const bool has_next = S.next(ui + 1, nxt);
;         const char* nA = has_next ? (const char*)g.A + (size_t)nxt.pm * tstepA : cA; const char* nB = has_next ? (const char*)g.Bt + (size_t)nxt.pn * tstepB : cB;
;     ...
; #pragma unroll
;         for (int a = 0; a < 2; ++a)
; #pragma unroll
;             for (int b = 0; b < 2; ++b)
; #pragma unroll
;                 for (int m = 0; m < 4; ++m)
; #pragma unroll
;                     for (int n = 0; n < 2; ++n) acc[a][b][m][n] = (f32x4){0.f, 0.f, 0.f, 0.f};
.LBB0_1076:
	s_ashr_i32 s19, s18, 31
	s_lshl_b64 s[20:21], s[18:19], 19
	s_add_u32 s20, s14, s20
	s_addc_u32 s21, s15, s21
	s_and_b64 s[24:25], s[0:1], exec
	s_cselect_b32 s19, s21, s29
	s_cselect_b32 s53, s20, s28
	s_ashr_i32 s13, s12, 31
	s_lshl_b64 s[24:25], s[12:13], 19
	s_add_u32 s24, s3, s24
	s_addc_u32 s25, s36, s25
	s_and_b64 s[34:35], s[0:1], exec
	s_cselect_b32 s13, s25, s31
	s_cselect_b32 s54, s24, s30
	s_add_u32 s28, s28, 0x40080
	s_addc_u32 s29, s29, 0
	s_add_u32 s55, s30, 0x100
	v_mov_b64_e32 v[0:1], 0
	v_mov_b64_e32 v[2:3], 0
	v_mov_b64_e32 v[4:5], 0
	v_mov_b64_e32 v[6:7], 0
	v_mov_b64_e32 v[8:9], 0
	v_mov_b64_e32 v[10:11], 0
	v_mov_b64_e32 v[12:13], 0
	v_mov_b64_e32 v[14:15], 0
	v_mov_b64_e32 v[16:17], 0
	v_mov_b64_e32 v[18:19], 0
	v_mov_b64_e32 v[20:21], 0
	v_mov_b64_e32 v[22:23], 0
	v_mov_b64_e32 v[24:25], 0
	v_mov_b64_e32 v[26:27], 0
	v_mov_b64_e32 v[28:29], 0
	v_mov_b64_e32 v[30:31], 0
	v_mov_b64_e32 v[32:33], 0
	v_mov_b64_e32 v[34:35], 0
	v_mov_b64_e32 v[36:37], 0
	v_mov_b64_e32 v[38:39], 0
	v_mov_b64_e32 v[40:41], 0
	v_mov_b64_e32 v[42:43], 0
	v_mov_b64_e32 v[44:45], 0
	v_mov_b64_e32 v[46:47], 0
	v_mov_b64_e32 v[48:49], 0
	v_mov_b64_e32 v[50:51], 0
	v_mov_b64_e32 v[52:53], 0
	v_mov_b64_e32 v[54:55], 0
	v_mov_b64_e32 v[56:57], 0
	v_mov_b64_e32 v[58:59], 0
	v_mov_b64_e32 v[60:61], 0
	v_mov_b64_e32 v[62:63], 0
	v_mov_b64_e32 v[64:65], 0
	v_mov_b64_e32 v[66:67], 0
	v_mov_b64_e32 v[68:69], 0
	v_mov_b64_e32 v[70:71], 0
	v_mov_b64_e32 v[72:73], 0
	v_mov_b64_e32 v[74:75], 0
	v_mov_b64_e32 v[76:77], 0
	v_mov_b64_e32 v[78:79], 0
	v_mov_b64_e32 v[80:81], 0
	v_mov_b64_e32 v[82:83], 0
	v_mov_b64_e32 v[84:85], 0
	v_mov_b64_e32 v[86:87], 0
	v_mov_b64_e32 v[88:89], 0
	v_mov_b64_e32 v[90:91], 0
	v_mov_b64_e32 v[92:93], 0
	v_mov_b64_e32 v[94:95], 0
	v_mov_b64_e32 v[96:97], 0
	v_mov_b64_e32 v[98:99], 0
	v_mov_b64_e32 v[100:101], 0
	v_mov_b64_e32 v[102:103], 0
	v_mov_b64_e32 v[104:105], 0
	v_mov_b64_e32 v[106:107], 0
	v_mov_b64_e32 v[108:109], 0
	v_mov_b64_e32 v[110:111], 0
	v_mov_b64_e32 v[112:113], 0
	v_mov_b64_e32 v[114:115], 0
	v_mov_b64_e32 v[116:117], 0
	v_mov_b64_e32 v[118:119], 0
	v_mov_b64_e32 v[120:121], 0
	v_mov_b64_e32 v[122:123], 0
	v_mov_b64_e32 v[124:125], 0
	v_mov_b64_e32 v[126:127], 0
	s_addc_u32 s56, s31, 0
	s_mov_b32 s57, -2

; template <class Epi, bool SP2 = false>
; __device__ __forceinline__ void gemm_phase(LAS unsigned char* lds, const Gemm g, const StaticOrder& S, const Epi& E) {
;     ...
;         const bool has_next = S.next(ui + 1, nxt);
;         const char* nA = has_next ? (const char*)g.A + (size_t)nxt.pm * tstepA : cA; const char* nB = has_next ? (const char*)g.Bt + (size_t)nxt.pn * tstepB : cB;
;     ...
; #pragma unroll
;         for (int a = 0; a < 2; ++a)
; #pragma unroll
;             for (int b = 0; b < 2; ++b)
; #pragma unroll
;                 for (int m = 0; m < 4; ++m)
; #pragma unroll
;                     for (int n = 0; n < 2; ++n) acc[a][b][m][n] = (f32x4){0.f, 0.f, 0.f, 0.f};
.LBB0_1147:
	s_add_u32 s30, s30, 0xb0080
	s_addc_u32 s31, s31, 0
	s_add_u32 s62, s34, 0x100
	v_mov_b64_e32 v[0:1], 0
	v_mov_b64_e32 v[2:3], 0
	v_mov_b64_e32 v[4:5], 0
	v_mov_b64_e32 v[6:7], 0
	v_mov_b64_e32 v[8:9], 0
	v_mov_b64_e32 v[10:11], 0
	v_mov_b64_e32 v[12:13], 0
	v_mov_b64_e32 v[14:15], 0
	v_mov_b64_e32 v[16:17], 0
	v_mov_b64_e32 v[18:19], 0
	v_mov_b64_e32 v[20:21], 0
	v_mov_b64_e32 v[22:23], 0
	v_mov_b64_e32 v[24:25], 0
	v_mov_b64_e32 v[26:27], 0
	v_mov_b64_e32 v[28:29], 0
	v_mov_b64_e32 v[30:31], 0
	v_mov_b64_e32 v[32:33], 0
	v_mov_b64_e32 v[34:35], 0
	v_mov_b64_e32 v[36:37], 0
	v_mov_b64_e32 v[38:39], 0
	v_mov_b64_e32 v[40:41], 0
	v_mov_b64_e32 v[42:43], 0
	v_mov_b64_e32 v[44:45], 0
	v_mov_b64_e32 v[46:47], 0
	v_mov_b64_e32 v[48:49], 0
	v_mov_b64_e32 v[50:51], 0
	v_mov_b64_e32 v[52:53], 0
	v_mov_b64_e32 v[54:55], 0
	v_mov_b64_e32 v[56:57], 0
	v_mov_b64_e32 v[58:59], 0
	v_mov_b64_e32 v[60:61], 0
	v_mov_b64_e32 v[62:63], 0
	v_mov_b64_e32 v[64:65], 0
	v_mov_b64_e32 v[66:67], 0
	v_mov_b64_e32 v[68:69], 0
	v_mov_b64_e32 v[70:71], 0
	v_mov_b64_e32 v[72:73], 0
	v_mov_b64_e32 v[74:75], 0
	v_mov_b64_e32 v[76:77], 0
	v_mov_b64_e32 v[78:79], 0
	v_mov_b64_e32 v[80:81], 0
	v_mov_b64_e32 v[82:83], 0
	v_mov_b64_e32 v[84:85], 0
	v_mov_b64_e32 v[86:87], 0
	v_mov_b64_e32 v[88:89], 0
	v_mov_b64_e32 v[90:91], 0
	v_mov_b64_e32 v[92:93], 0
	v_mov_b64_e32 v[94:95], 0
	v_mov_b64_e32 v[96:97], 0
	v_mov_b64_e32 v[98:99], 0
	v_mov_b64_e32 v[100:101], 0
	v_mov_b64_e32 v[102:103], 0
	v_mov_b64_e32 v[104:105], 0
	v_mov_b64_e32 v[106:107], 0
	v_mov_b64_e32 v[108:109], 0
	v_mov_b64_e32 v[110:111], 0
	v_mov_b64_e32 v[112:113], 0
	v_mov_b64_e32 v[114:115], 0
	v_mov_b64_e32 v[116:117], 0
	v_mov_b64_e32 v[118:119], 0
	v_mov_b64_e32 v[120:121], 0
	v_mov_b64_e32 v[122:123], 0
	v_mov_b64_e32 v[124:125], 0
	v_mov_b64_e32 v[126:127], 0
	s_addc_u32 s63, s35, 0
	s_mov_b32 s64, -2
